# P0 x->out residual copy: 8 loads in flight per thread (4 rounds of 8) instead of one load-wait-store per iteration (on top of v33)
# speedup vs baseline: 1.0031x; 1.0031x over previous
.LBB0_71:
	s_or_b64 exec, exec, s[2:3]
	v_lshl_add_u64 v[0:1], s[10:11], 0, v[132:133]
	s_mov_b64 s[0:1], 0x400000
	v_cmp_gt_u64_e32 vcc, s[0:1], v[0:1]
	s_mov_b64 s[2:3], exec
	v_readlane_b32 s16, v249, 34
	v_readlane_b32 s17, v249, 35
	v_readlane_b32 s18, v249, 36
	v_readlane_b32 s19, v249, 37
	v_readlane_b32 s20, v249, 38
	v_readlane_b32 s21, v249, 39
	v_readlane_b32 s22, v249, 40
	v_readlane_b32 s23, v249, 41
	v_readlane_b32 s24, v249, 42
	v_readlane_b32 s25, v249, 43
	v_readlane_b32 s26, v249, 44
	v_readlane_b32 s27, v249, 45
	v_readlane_b32 s12, v249, 2
	s_and_b64 s[0:1], s[2:3], vcc
	v_readlane_b32 s30, v249, 48
	v_readlane_b32 s31, v249, 49
	v_readlane_b32 s13, v249, 3
	v_readlane_b32 s28, v249, 46
	v_readlane_b32 s29, v249, 47
	v_readlane_b32 s14, v249, 4
	v_readlane_b32 s15, v249, 5
	v_readlane_b32 s16, v249, 6
	v_readlane_b32 s17, v249, 7
	v_readlane_b32 s18, v249, 8
	v_readlane_b32 s19, v249, 9
	v_readlane_b32 s20, v249, 10
	v_readlane_b32 s21, v249, 11
	v_readlane_b32 s22, v249, 12
	v_readlane_b32 s23, v249, 13
	v_readlane_b32 s24, v249, 14
	v_readlane_b32 s25, v249, 15
	v_readlane_b32 s26, v249, 16
	v_readlane_b32 s27, v249, 17
	s_mov_b64 exec, s[0:1]
	s_cbranch_execz .LBB0_74
	s_ashr_i32 s1, s94, 31
	s_mov_b32 s0, s94
	s_lshl_b64 s[6:7], s[52:53], 13
	s_lshl_b64 s[4:5], s[0:1], 9
	v_lshl_add_u64 v[2:3], v[132:133], 4, s[6:7]
	s_lshl_b64 s[6:7], s[0:1], 13
	s_mov_b64 s[8:9], 0
	s_mov_b64 s[10:11], 0x3fffff
	v_mov_b64_e32 v[4:5], v[0:1]
	s_cmp_eq_u32 s94, 0x100
	s_cbranch_scc0 .LBB0_73
	s_mov_b32 s8, 4
	s_sub_u32 s10, s30, s12
	s_subb_u32 s11, s31, s13
.Lxc_loop:
	v_lshl_add_u64 v[20:21], s[12:13], 0, v[2:3]
	global_load_dwordx4 v[40:43], v[20:21], off
	v_lshl_add_u64 v[2:3], v[2:3], 0, s[6:7]
	v_lshl_add_u64 v[22:23], s[12:13], 0, v[2:3]
	global_load_dwordx4 v[44:47], v[22:23], off
	v_lshl_add_u64 v[2:3], v[2:3], 0, s[6:7]
	v_lshl_add_u64 v[24:25], s[12:13], 0, v[2:3]
	global_load_dwordx4 v[48:51], v[24:25], off
	v_lshl_add_u64 v[2:3], v[2:3], 0, s[6:7]
	v_lshl_add_u64 v[26:27], s[12:13], 0, v[2:3]
	global_load_dwordx4 v[52:55], v[26:27], off
	v_lshl_add_u64 v[2:3], v[2:3], 0, s[6:7]
	v_lshl_add_u64 v[28:29], s[12:13], 0, v[2:3]
	global_load_dwordx4 v[56:59], v[28:29], off
	v_lshl_add_u64 v[2:3], v[2:3], 0, s[6:7]
	v_lshl_add_u64 v[30:31], s[12:13], 0, v[2:3]
	global_load_dwordx4 v[60:63], v[30:31], off
	v_lshl_add_u64 v[2:3], v[2:3], 0, s[6:7]
	v_lshl_add_u64 v[32:33], s[12:13], 0, v[2:3]
	global_load_dwordx4 v[64:67], v[32:33], off
	v_lshl_add_u64 v[2:3], v[2:3], 0, s[6:7]
	v_lshl_add_u64 v[34:35], s[12:13], 0, v[2:3]
	global_load_dwordx4 v[68:71], v[34:35], off
	v_lshl_add_u64 v[2:3], v[2:3], 0, s[6:7]
	v_lshl_add_u64 v[20:21], v[20:21], 0, s[10:11]
	s_waitcnt vmcnt(7)
	global_store_dwordx4 v[20:21], v[40:43], off
	v_lshl_add_u64 v[22:23], v[22:23], 0, s[10:11]
	s_waitcnt vmcnt(7)
	global_store_dwordx4 v[22:23], v[44:47], off
	v_lshl_add_u64 v[24:25], v[24:25], 0, s[10:11]
	s_waitcnt vmcnt(7)
	global_store_dwordx4 v[24:25], v[48:51], off
	v_lshl_add_u64 v[26:27], v[26:27], 0, s[10:11]
	s_waitcnt vmcnt(7)
	global_store_dwordx4 v[26:27], v[52:55], off
	v_lshl_add_u64 v[28:29], v[28:29], 0, s[10:11]
	s_waitcnt vmcnt(7)
	global_store_dwordx4 v[28:29], v[56:59], off
	v_lshl_add_u64 v[30:31], v[30:31], 0, s[10:11]
	s_waitcnt vmcnt(7)
	global_store_dwordx4 v[30:31], v[60:63], off
	v_lshl_add_u64 v[32:33], v[32:33], 0, s[10:11]
	s_waitcnt vmcnt(7)
	global_store_dwordx4 v[32:33], v[64:67], off
	v_lshl_add_u64 v[34:35], v[34:35], 0, s[10:11]
	s_waitcnt vmcnt(7)
	global_store_dwordx4 v[34:35], v[68:71], off
	s_sub_i32 s8, s8, 1
	s_cmp_lg_u32 s8, 0
	s_cbranch_scc1 .Lxc_loop
	s_branch .LBB0_74
